# snake MFMA order + strips wait only for Q rows + L2 touch-prefetch of next DL strip first K/V tile
# baseline (speedup 1.0000x reference)
.LBB0_253:
	v_mov_b32_e32 v66, 0
	s_andn2_b64 vcc, exec, s[0:1]
	v_mov_b32_e32 v67, v66
	v_mov_b32_e32 v68, v66
	v_mov_b32_e32 v69, v66
	v_mov_b32_e32 v70, v66
	v_mov_b32_e32 v71, v66
	v_mov_b32_e32 v72, v66
	v_mov_b32_e32 v73, v66
	v_mov_b32_e32 v78, v66
	v_mov_b32_e32 v79, v66
	v_mov_b32_e32 v80, v66
	v_mov_b32_e32 v81, v66
	v_mov_b32_e32 v74, v66
	v_mov_b32_e32 v75, v66
	v_mov_b32_e32 v76, v66
	v_mov_b32_e32 v77, v66
	v_mov_b32_e32 v86, v66
	v_mov_b32_e32 v87, v66
	v_mov_b32_e32 v88, v66
	v_mov_b32_e32 v89, v66
	v_mov_b32_e32 v82, v66
	v_mov_b32_e32 v83, v66
	v_mov_b32_e32 v84, v66
	v_mov_b32_e32 v85, v66
	v_mov_b32_e32 v94, v66
	v_mov_b32_e32 v95, v66
	v_mov_b32_e32 v96, v66
	v_mov_b32_e32 v97, v66
	v_mov_b32_e32 v90, v66
	v_mov_b32_e32 v91, v66
	v_mov_b32_e32 v92, v66
	v_mov_b32_e32 v93, v66
	s_cbranch_vccnz .LBB0_255
	s_ff1_i32_b32 s56, s15
	s_lshr_b32 s57, s31, s56
	s_addk_i32 s57, 0xff80
	s_max_i32 s57, s57, 0
	s_and_b32 s57, s57, 0xffffffc0
	s_lshl_b32 s57, s57, s56
	s_add_i32 s58, s15, -1
	s_and_b32 s58, s31, s58
	s_add_i32 s57, s57, s58
	s_lshl_b32 s58, s26, 1
	s_addk_i32 s58, 0xc00
	s_add_u32 s58, s10, s58
	s_addc_u32 s59, s11, 0
	v_mul_lo_u32 v242, v173, s15
	v_add_u32_e32 v242, s57, v242
	v_mad_u64_u32 v[242:243], s[60:61], v242, v223, s[58:59]
	global_load_dword v244, v[242:243], off
	global_load_dword v244, v[242:243], off offset:128
	global_load_dword v244, v[242:243], off offset:3072
	global_load_dword v244, v[242:243], off offset:3200
	s_mul_i32 s0, s15, 0x2800
	v_mul_lo_u32 v0, s0, v177
	v_and_b32_e32 v66, 0x78, v190
	v_add3_u32 v0, v66, s26, v0
	s_lshl_b32 s0, s15, 2
	v_lshl_add_u64 v[90:91], v[0:1], 1, s[10:11]
	s_mul_i32 s26, s31, 0x2800
	s_add_i32 s1, s0, s31
	v_lshl_add_u64 v[66:67], s[26:27], 1, v[90:91]
	s_mul_i32 s26, s1, 0x2800
	s_add_i32 s1, s1, s0
	v_lshl_add_u64 v[70:71], s[26:27], 1, v[90:91]
	s_mul_i32 s26, s1, 0x2800
	s_add_i32 s1, s1, s0
	v_lshl_add_u64 v[74:75], s[26:27], 1, v[90:91]
	s_mul_i32 s26, s1, 0x2800
	s_add_i32 s1, s1, s0
	v_lshl_add_u64 v[76:77], s[26:27], 1, v[90:91]
	s_mul_i32 s26, s1, 0x2800
	s_add_i32 s1, s1, s0
	v_lshl_add_u64 v[82:83], s[26:27], 1, v[90:91]
	s_mul_i32 s26, s1, 0x2800
	s_add_i32 s1, s1, s0
	v_lshl_add_u64 v[84:85], s[26:27], 1, v[90:91]
	s_mul_i32 s26, s1, 0x2800
	s_add_i32 s0, s1, s0
	v_lshl_add_u64 v[92:93], s[26:27], 1, v[90:91]
	s_mul_i32 s26, s0, 0x2800
	v_lshl_add_u64 v[90:91], s[26:27], 1, v[90:91]
	global_load_dwordx4 v[66:69], v[66:67], off
	s_nop 0
	global_load_dwordx4 v[70:73], v[70:71], off
	s_nop 0
	global_load_dwordx4 v[78:81], v[74:75], off
	s_nop 0
	global_load_dwordx4 v[74:77], v[76:77], off
	s_nop 0
	global_load_dwordx4 v[86:89], v[82:83], off
	s_nop 0
	global_load_dwordx4 v[82:85], v[84:85], off
	s_nop 0
	global_load_dwordx4 v[94:97], v[92:93], off
	s_nop 0
	global_load_dwordx4 v[90:93], v[90:91], off
